# mLSTM prep step 1: five small loads hoisted ahead of tile loads (1 round trip instead of 4)
# speedup vs baseline: 1.0421x; 1.0014x over previous
; #define LAS __attribute__((address_space(3)))
; __device__ __forceinline__ float logsigf_(float x) { return x >= 0.f ? -flog1p(fexp(-x)) : x - flog1p(fexp(x)); }
; __device__ __forceinline__ void mlstm_prep_unit(const Frame& F, int l, int u) {
;     ...
;     {
;         const int r = t >> 3, seg = t & 7; const bf16_t* zr = F.Z + (size_t)(row0 + r) * ZW + h * 64 + seg * 8;
;         const v4u q = *(const v4u*)(zr + ZC_LQ), k = *(const v4u*)(zr + ZC_LK), v = *(const v4u*)(zr + ZC_LV);
;         *(LAS v4u*)(Qs + r * 72 + seg * 8) = q; *(LAS v4u*)(Ks + r * 72 + seg * 8) = k;
;         Vta[( 0 + 2 * seg) * 72 + r] = (bf16_t)(v.x & 0xffffu); Vta[(16 + 2 * seg) * 72 + r] = (bf16_t)(v.x >> 16);
;         Vta[(32 + 2 * seg) * 72 + r] = (bf16_t)(v.y & 0xffffu); Vta[(48 + 2 * seg) * 72 + r] = (bf16_t)(v.y >> 16);
;         Vta[( 1 + 2 * seg) * 72 + r] = (bf16_t)(v.z & 0xffffu); Vta[(17 + 2 * seg) * 72 + r] = (bf16_t)(v.z >> 16);
;         Vta[(33 + 2 * seg) * 72 + r] = (bf16_t)(v.w & 0xffffu); Vta[(49 + 2 * seg) * 72 + r] = (bf16_t)(v.w >> 16);
; #pragma unroll
;         for (int j = 0; j < 2; ++j) { const int idx = t + 512 * j, rr = 64 + (idx >> 6), cc = idx & 63; Vta[rr * 72 + cc] = (bf16_t)(rr == 64 ? 0x3F80u : 0u); }
;         if (t < 128) { const int d = t >> 6, p = t & 63; const bf16_t* zg = F.Z + (size_t)(row0 + p) * ZW;
;             igS[d * 64 + p] = bf2f(zg[ZC_LI + d * 4 + h]) + F.ig_bias[l * 8 + d * 4 + h];
;             lfS[d * 64 + p] = logsigf_(bf2f(zg[ZC_LF + d * 4 + h]) + F.fg_bias[l * 8 + d * 4 + h]); }
;         if (t >= 128 && t < 272) chS[t - 128] = F.CHS[(size_t)((b * 4 + h) * 2) * 72 + (t - 128)];
.LBB0_694:
	s_waitcnt vmcnt(9)
	v_mbcnt_lo_u32_b32 v58, -1, 0
	v_mbcnt_hi_u32_b32 v58, -1, v58
	s_and_b32 s6, s3, 3
	v_add_u32_e32 v2, s64, v58
	v_ashrrev_i32_e32 v18, 3, v2
	v_add_u32_e32 v0, s7, v18
	v_mov_b64_e32 v[4:5], s[16:17]
	v_and_b32_e32 v3, 7, v58
	v_mad_i64_i32 v[4:5], s[8:9], v0, s66, v[4:5]
	s_lshl_b32 s92, s6, 7
	v_lshl_add_u64 v[4:5], v[4:5], 0, s[92:93]
	v_lshlrev_b32_e32 v0, 4, v3
	v_lshl_add_u64 v[4:5], v[4:5], 0, v[0:1]
	s_movk_i32 s3, 0x1000
	v_add_co_u32_e32 v4, vcc, s3, v4
	v_add_u32_e32 v20, 0x200, v2
	s_nop 0
	v_addc_co_u32_e32 v5, vcc, 0, v5, vcc
	v_cmp_gt_i32_e32 vcc, 0x80, v2
	s_and_saveexec_b64 s[10:11], vcc
	s_cbranch_execz .Lmpf_a
	v_add_u32_e32 v144, s7, v58
	v_mov_b64_e32 v[146:147], s[16:17]
	v_mad_i64_i32 v[146:147], s[8:9], v144, s66, v[146:147]
	v_ashrrev_i32_e32 v144, 6, v2
	v_lshlrev_b32_e32 v144, 2, v144
	v_or_b32_e32 v145, s6, v144
	v_add_u32_e32 v148, 0xc10, v145
	v_ashrrev_i32_e32 v149, 31, v148
	v_lshl_add_u64 v[146:147], v[148:149], 1, v[146:147]
	global_load_ushort v150, v[146:147], off
	global_load_ushort v151, v[146:147], off offset:16
	v_add_u32_e32 v144, s68, v144
	v_or_b32_e32 v148, s6, v144
	v_ashrrev_i32_e32 v149, 31, v148
	v_lshlrev_b64 v[148:149], 2, v[148:149]
	v_lshl_add_u64 v[146:147], s[52:53], 0, v[148:149]
	global_load_dword v152, v[146:147], off
	v_lshl_add_u64 v[146:147], s[54:55], 0, v[148:149]
	global_load_dword v154, v[146:147], off
.Lmpf_a:
	s_or_b64 exec, exec, s[10:11]
	v_add_u32_e32 v145, 0xffffff80, v2
	v_cmp_gt_u32_e32 vcc, 0x90, v145
	s_and_saveexec_b64 s[10:11], vcc
	s_cbranch_execz .Lmpf_b
	s_lshl_b32 s12, s5, 3
	s_lshl_b32 s13, s6, 1
	s_or_b32 s12, s13, s12
	s_mul_hi_i32 s13, s12, 0x120
	s_mulk_i32 s12, 0x120
	s_add_u32 s12, s18, s12
	s_addc_u32 s13, s19, s13
	v_mov_b32_e32 v146, v145
	v_mov_b32_e32 v147, 0
	v_lshl_add_u64 v[146:147], v[146:147], 2, s[12:13]
	global_load_dword v155, v[146:147], off
.Lmpf_b:
	s_or_b64 exec, exec, s[10:11]
	global_load_dwordx4 v[6:9], v[4:5], off
	global_load_dwordx4 v[10:13], v[4:5], off offset:512
	global_load_dwordx4 v[14:17], v[4:5], off offset:1024
	s_movk_i32 s8, 0x90
	v_ashrrev_i32_e32 v4, 6, v2
	v_cmp_gt_u32_e32 vcc, 64, v2
	v_mul_lo_u32 v21, v18, s8
	v_ashrrev_i32_e32 v23, 6, v20
	v_and_b32_e32 v62, 63, v58
	v_cndmask_b32_e32 v19, 0, v230, vcc
	v_mul_lo_u32 v22, v4, s8
	v_cmp_gt_u32_e32 vcc, 64, v20
	v_add3_u32 v0, 0, v21, v0
	v_mul_lo_u32 v21, v23, s8
	s_movk_i32 s8, 0x80
	v_mul_u32_u24_e32 v5, 0x120, v3
	v_lshlrev_b32_e32 v3, 1, v62
	v_readfirstlane_b32 s3, v4
	v_lshlrev_b32_e32 v18, 1, v18
	v_cndmask_b32_e32 v20, 0, v230, vcc
	v_cmp_gt_i32_e32 vcc, s8, v2
	v_add3_u32 v5, 0, v5, v18
	v_add3_u32 v18, 0, v22, v3
	v_add3_u32 v21, 0, v21, v3
	s_waitcnt vmcnt(2)
	ds_write_b128 v0, v[6:9]
	s_waitcnt vmcnt(1)
	ds_write_b128 v0, v[10:13] offset:9216
	s_waitcnt vmcnt(0)
	ds_write_b16 v5, v14 offset:18432
	ds_write_b16_d16_hi v5, v14 offset:20736
	ds_write_b16 v5, v15 offset:23040
	ds_write_b16_d16_hi v5, v15 offset:25344
	ds_write_b16 v5, v16 offset:18576
	ds_write_b16_d16_hi v5, v16 offset:20880
	ds_write_b16 v5, v17 offset:23184
	ds_write_b16_d16_hi v5, v17 offset:25488
	ds_write_b16 v18, v19 offset:27648
	ds_write_b16 v21, v20 offset:27648
	s_and_saveexec_b64 s[10:11], vcc
	s_cbranch_execz .LBB0_708
	v_lshlrev_b32_e32 v11, 16, v150
	s_waitcnt lgkmcnt(0)
	v_add_f32_e32 v8, v152, v11
	v_lshl_add_u32 v0, v2, 2, 0
	v_add_u32_e32 v9, 0x10500, v0
	ds_write_b32 v9, v8
	v_lshlrev_b32_e32 v6, 16, v151
	v_add_f32_e32 v4, v154, v6
	v_cmp_le_f32_e32 vcc, 0, v4
	s_and_saveexec_b64 s[8:9], vcc
	s_xor_b64 s[12:13], exec, s[8:9]
	s_cbranch_execz .LBB0_701
	v_mul_f32_e32 v4, 0xbfb8aa3b, v4
	v_exp_f32_e32 v4, v4
	s_mov_b32 s7, 0x3ca3d70a
	v_cmp_ngt_f32_e32 vcc, s7, v4
	s_and_saveexec_b64 s[8:9], vcc
	s_xor_b64 s[14:15], exec, s[8:9]
	v_add_f32_e32 v4, 1.0, v4
	v_log_f32_e32 v4, v4
	s_nop 0
	v_mul_f32_e32 v5, 0x3f317218, v4
	s_andn2_saveexec_b64 s[14:15], s[14:15]
	v_fmamk_f32 v5, v4, 0xbe800000, v222
	v_fma_f32 v5, -v4, v5, 0.5
	v_fma_f32 v5, -v4, v5, 1.0
	v_mul_f32_e32 v5, v4, v5
	s_or_b64 exec, exec, s[14:15]
	v_xor_b32_e32 v5, 0x80000000, v5

; __device__ __forceinline__ void mlstm_prep_unit(const Frame& F, int l, int u) {
;     ...
;         if (t >= 128 && t < 272) chS[t - 128] = F.CHS[(size_t)((b * 4 + h) * 2) * 72 + (t - 128)];
.LBB0_708:
	s_or_b64 exec, exec, s[10:11]
	v_add_u32_e32 v0, 0xffffff80, v2
	s_movk_i32 s7, 0x90
	v_cmp_gt_u32_e32 vcc, s7, v0
	s_and_saveexec_b64 s[10:11], vcc
	s_cbranch_execz .LBB0_710
	v_lshl_add_u32 v0, v0, 2, 0
	v_add_u32_e32 v0, 0x11320, v0
	ds_write_b32 v0, v155
